# ret_u items (rec_state): K/V staging loads issued up to three iterations ahead into spare registers with counted waits
# speedup vs baseline: 1.0618x; 1.0029x over previous
; DI float bf2f(unsigned h) { return __uint_as_float(h << 16); }
; DI float ex2(float x) { return __builtin_amdgcn_exp2f(x); }
; DI int opqv(int x) { asm volatile("" : "+v"(x)); return x; }
; DI char* opq(char* p) { asm volatile("" : "+s"(p)); return p; }
; DI float lg2gamma(int h) { return log2f(1.0f - exp2f(-5.0f - (float)h)); }
; DI void ret_u_item(const Params& p, int b, int n, int h, char* smem) {
;   const int tid = opqv(threadIdx.x) & 255, lane = tid & 63, w = tid >> 6, wm = w >> 1, wn = w & 1, l32 = lane & 31, hf = lane >> 5;
;   char* ws = opq(p.ws);
;   const u16* zr = (const u16*)(ws + OFF_ZR); float* U = (float*)(ws + OFF_UO);
;   char* sKt = smem; char* sVt = smem + 128 * 272;
;   const size_t t0 = (size_t)b * S_ + n * 128;
;   const float lg = lg2gamma(h);
; #pragma unroll
;   for (int i = 0; i < 8; ++i) {
;     const int c = tid + 256 * i, row = c >> 4, ch = c & 15;
;     const uint4 kv = *(const uint4*)(zr + (t0 + row) * LDZR + 512 + h * 128 + ch * 8);
;     const uint4 vv = *(const uint4*)(zr + (t0 + row) * LDZR + 1024 + h * 128 + ch * 8);
;     const float te = ex2((float)(127 - row) * lg);
;     char* kb = sKt + (ch * 8) * 272 + row * 2; char* vb = sVt + (ch * 8) * 272 + row * 2;
;     *(u16*)(kb + 0 * 272) = f2bf(bf2f(kv.x & 0xffffu) * te); *(u16*)(kb + 1 * 272) = f2bf(bf2f(kv.x >> 16) * te);
;     *(u16*)(kb + 2 * 272) = f2bf(bf2f(kv.y & 0xffffu) * te); *(u16*)(kb + 3 * 272) = f2bf(bf2f(kv.y >> 16) * te);
;     *(u16*)(kb + 4 * 272) = f2bf(bf2f(kv.z & 0xffffu) * te); *(u16*)(kb + 5 * 272) = f2bf(bf2f(kv.z >> 16) * te);
;     *(u16*)(kb + 6 * 272) = f2bf(bf2f(kv.w & 0xffffu) * te); *(u16*)(kb + 7 * 272) = f2bf(bf2f(kv.w >> 16) * te);
;     *(u16*)(vb + 0 * 272) = (u16)(vv.x & 0xffffu); *(u16*)(vb + 1 * 272) = (u16)(vv.x >> 16);
;     *(u16*)(vb + 2 * 272) = (u16)(vv.y & 0xffffu); *(u16*)(vb + 3 * 272) = (u16)(vv.y >> 16);
;     *(u16*)(vb + 4 * 272) = (u16)(vv.z & 0xffffu); *(u16*)(vb + 5 * 272) = (u16)(vv.z >> 16);
;     *(u16*)(vb + 6 * 272) = (u16)(vv.w & 0xffffu); *(u16*)(vb + 7 * 272) = (u16)(vv.w >> 16);
;   }
.LBB0_766:
	v_and_b32_e32 v11, 3, v68
	v_cvt_f32_ubyte0_e32 v2, v11
	v_sub_f32_e32 v2, 0xc0a00000, v2
	v_cmp_gt_f32_e32 vcc, s15, v2
	v_ashrrev_i32_e32 v0, 9, v68
	v_mov_b32_e32 v6, v182
	v_cndmask_b32_e32 v3, 0, v200, vcc
	v_add_f32_e32 v2, v2, v3
	v_exp_f32_e32 v2, v2
	v_cndmask_b32_e32 v3, 0, v192, vcc
	s_mov_b64 s[0:1], s[10:11]
	s_waitcnt lgkmcnt(0)
	v_ashrrev_i32_e32 v1, 31, v0
	v_ldexp_f32 v2, v2, v3
	v_sub_f32_e32 v2, 1.0, v2
	v_cmp_gt_f32_e32 vcc, s59, v2
	v_bfe_u32 v64, v68, 2, 7
	s_add_u32 s8, s0, 0xd004100
	v_cndmask_b32_e64 v3, 0, 32, vcc
	v_ldexp_f32 v2, v2, v3
	v_log_f32_e32 v2, v2
	v_lshlrev_b64 v[0:1], 14, v[0:1]
	v_cndmask_b32_e32 v3, 0, v193, vcc
	s_addc_u32 s9, s1, 0
	v_lshl_or_b32 v0, v64, 7, v0
	v_sub_f32_e32 v7, v2, v3
	v_lshlrev_b32_e32 v2, 3, v6
	v_bfe_u32 v10, v6, 4, 4
	v_and_b32_e32 v14, 0x78, v2
	v_or_b32_e32 v4, v0, v10
	v_mov_b64_e32 v[2:3], s[8:9]
	v_mad_u64_u32 v[4:5], s[8:9], v4, s14, v[2:3]
	v_mad_i32_i24 v5, v1, s14, v5
	v_lshlrev_b32_e32 v160, 8, v11
	v_lshl_add_u64 v[12:13], v[4:5], 0, v[160:161]
	v_lshlrev_b32_e32 v4, 1, v14
	v_mov_b32_e32 v5, v161
	v_lshl_add_u64 v[16:17], v[12:13], 0, v[4:5]
	v_mad_u32_u24 v8, v14, s20, v67
	s_waitcnt vmcnt(0)
	global_load_dwordx4 v[12:15], v[16:17], off offset:1024
	s_nop 0
	global_load_dwordx4 v[16:19], v[16:17], off offset:2048
	v_or_b32_e32 v23, 16, v10
	v_or_b32_e32 v24, v0, v23
	v_mad_u64_u32 v[24:25], s[8:9], v24, s14, v[2:3]
	v_mad_i32_i24 v25, v1, s14, v25
	v_lshl_add_u64 v[24:25], v[24:25], 0, v[160:161]
	v_lshl_add_u64 v[28:29], v[24:25], 0, v[4:5]
	global_load_dwordx4 v[24:27], v[28:29], off offset:1024
	s_nop 0
	global_load_dwordx4 v[28:31], v[28:29], off offset:2048
	v_or_b32_e32 v35, 32, v10
	v_or_b32_e32 v36, v0, v35
	v_mad_u64_u32 v[36:37], s[8:9], v36, s14, v[2:3]
	v_mad_i32_i24 v37, v1, s14, v37
	v_lshl_add_u64 v[36:37], v[36:37], 0, v[160:161]
	v_lshl_add_u64 v[40:41], v[36:37], 0, v[4:5]
	global_load_dwordx4 v[36:39], v[40:41], off offset:1024
	s_nop 0
	global_load_dwordx4 v[40:43], v[40:41], off offset:2048
	v_or_b32_e32 v47, 48, v10
	v_or_b32_e32 v48, v0, v47
	v_mad_u64_u32 v[48:49], s[8:9], v48, s14, v[2:3]
	v_mad_i32_i24 v49, v1, s14, v49
	v_lshl_add_u64 v[48:49], v[48:49], 0, v[160:161]
	v_lshl_add_u64 v[52:53], v[48:49], 0, v[4:5]
	global_load_dwordx4 v[48:51], v[52:53], off offset:1024
	s_nop 0
	global_load_dwordx4 v[52:55], v[52:53], off offset:2048
	v_lshrrev_b32_e32 v9, 4, v6
	v_lshlrev_b32_e32 v65, 7, v11
	v_bitop3_b32 v11, v9, s13, 15 bitop3:0x6c
	v_cvt_f32_ubyte0_e32 v11, v11
	v_mul_f32_e32 v11, v7, v11
	v_exp_f32_e32 v11, v11
	v_lshl_add_u32 v20, v10, 1, v8
	s_movk_i32 s7, 0x6f
	v_bfe_u32 v71, v6, 5, 1
	v_and_b32_e32 v70, 0x5f, v6
	v_or_b32_e32 v69, 32, v70
	s_add_i32 s6, s6, s16
	s_cmpk_gt_i32 s6, 0x1ff
	s_waitcnt vmcnt(6) lgkmcnt(0)
	v_lshlrev_b32_e32 v21, 16, v12
	v_and_b32_e32 v12, 0xffff0000, v12
	v_mul_f32_e32 v12, v11, v12
	v_cvt_pk_bf16_f32 v12, v12, s0
	ds_write_b16 v20, v12 offset:272
	v_lshlrev_b32_e32 v12, 16, v13
	v_mul_f32_e32 v12, v11, v12
	v_cvt_pk_bf16_f32 v12, v12, s0
	ds_write_b16 v20, v12 offset:544
	v_and_b32_e32 v12, 0xffff0000, v13
	v_mul_f32_e32 v12, v11, v12
	v_cvt_pk_bf16_f32 v12, v12, s0
	ds_write_b16 v20, v12 offset:816
	v_lshlrev_b32_e32 v12, 16, v14
	v_mul_f32_e32 v12, v11, v12
	v_cvt_pk_bf16_f32 v12, v12, s0
	ds_write_b16 v20, v12 offset:1088
	v_and_b32_e32 v12, 0xffff0000, v14
	v_mul_f32_e32 v12, v11, v12
	v_cvt_pk_bf16_f32 v12, v12, s0
	ds_write_b16 v20, v12 offset:1360
	v_lshlrev_b32_e32 v12, 16, v15
	v_mul_f32_e32 v12, v11, v12
	v_cvt_pk_bf16_f32 v12, v12, s0
	ds_write_b16 v20, v12 offset:1632
	v_and_b32_e32 v12, 0xffff0000, v15
	v_mul_f32_e32 v21, v11, v21
	v_mul_f32_e32 v11, v11, v12
	v_cvt_pk_bf16_f32 v21, v21, s0
	v_cvt_pk_bf16_f32 v11, v11, s0
	ds_write_b16 v20, v21
	ds_write_b16 v20, v11 offset:1904
	ds_write_b16 v20, v16 offset:34816
	ds_write_b16_d16_hi v20, v16 offset:35088
	ds_write_b16 v20, v17 offset:35360
	ds_write_b16_d16_hi v20, v17 offset:35632
	ds_write_b16 v20, v18 offset:35904
	ds_write_b16_d16_hi v20, v18 offset:36176
	ds_write_b16 v20, v19 offset:36448
	ds_write_b16_d16_hi v20, v19 offset:36720
	v_or_b32_e32 v11, 64, v10
	v_or_b32_e32 v12, v0, v11
	v_mad_u64_u32 v[12:13], s[8:9], v12, s14, v[2:3]
	v_mad_i32_i24 v13, v1, s14, v13
	v_lshl_add_u64 v[12:13], v[12:13], 0, v[160:161]
	v_lshl_add_u64 v[16:17], v[12:13], 0, v[4:5]
	global_load_dwordx4 v[12:15], v[16:17], off offset:1024
	s_nop 0
	global_load_dwordx4 v[16:19], v[16:17], off offset:2048
	v_bitop3_b32 v32, v9, s7, 15 bitop3:0x6c
	v_cvt_f32_ubyte0_e32 v32, v32
	v_mul_f32_e32 v32, v7, v32
	v_exp_f32_e32 v32, v32
	v_lshl_add_u32 v23, v23, 1, v8
	s_movk_i32 s7, 0x5f
	s_waitcnt vmcnt(6) lgkmcnt(0)
; DI float bf2f(unsigned h) { return __uint_as_float(h << 16); }
; DI float ex2(float x) { return __builtin_amdgcn_exp2f(x); }
; DI void ret_u_item(const Params& p, int b, int n, int h, char* smem) {
;     ...
;   for (int i = 0; i < 8; ++i) {
;     const int c = tid + 256 * i, row = c >> 4, ch = c & 15;
;     const uint4 kv = *(const uint4*)(zr + (t0 + row) * LDZR + 512 + h * 128 + ch * 8);
;     const uint4 vv = *(const uint4*)(zr + (t0 + row) * LDZR + 1024 + h * 128 + ch * 8);
;     const float te = ex2((float)(127 - row) * lg);
;     char* kb = sKt + (ch * 8) * 272 + row * 2; char* vb = sVt + (ch * 8) * 272 + row * 2;
;     *(u16*)(kb + 0 * 272) = f2bf(bf2f(kv.x & 0xffffu) * te); *(u16*)(kb + 1 * 272) = f2bf(bf2f(kv.x >> 16) * te);
;     *(u16*)(kb + 2 * 272) = f2bf(bf2f(kv.y & 0xffffu) * te); *(u16*)(kb + 3 * 272) = f2bf(bf2f(kv.y >> 16) * te);
;     *(u16*)(kb + 4 * 272) = f2bf(bf2f(kv.z & 0xffffu) * te); *(u16*)(kb + 5 * 272) = f2bf(bf2f(kv.z >> 16) * te);
;     *(u16*)(kb + 6 * 272) = f2bf(bf2f(kv.w & 0xffffu) * te); *(u16*)(kb + 7 * 272) = f2bf(bf2f(kv.w >> 16) * te);
;     *(u16*)(vb + 0 * 272) = (u16)(vv.x & 0xffffu); *(u16*)(vb + 1 * 272) = (u16)(vv.x >> 16);
;     *(u16*)(vb + 2 * 272) = (u16)(vv.y & 0xffffu); *(u16*)(vb + 3 * 272) = (u16)(vv.y >> 16);
;     *(u16*)(vb + 4 * 272) = (u16)(vv.z & 0xffffu); *(u16*)(vb + 5 * 272) = (u16)(vv.z >> 16);
;     *(u16*)(vb + 6 * 272) = (u16)(vv.w & 0xffffu); *(u16*)(vb + 7 * 272) = (u16)(vv.w >> 16);
	v_lshlrev_b32_e32 v33, 16, v24
	v_and_b32_e32 v24, 0xffff0000, v24
	v_mul_f32_e32 v24, v32, v24
	v_cvt_pk_bf16_f32 v24, v24, s0
	ds_write_b16 v23, v24 offset:272
	v_lshlrev_b32_e32 v24, 16, v25
	v_mul_f32_e32 v24, v32, v24
	v_cvt_pk_bf16_f32 v24, v24, s0
	ds_write_b16 v23, v24 offset:544
	v_and_b32_e32 v24, 0xffff0000, v25
	v_mul_f32_e32 v24, v32, v24
	v_cvt_pk_bf16_f32 v24, v24, s0
	ds_write_b16 v23, v24 offset:816
	v_lshlrev_b32_e32 v24, 16, v26
	v_mul_f32_e32 v24, v32, v24
	v_cvt_pk_bf16_f32 v24, v24, s0
	ds_write_b16 v23, v24 offset:1088
	v_and_b32_e32 v24, 0xffff0000, v26
	v_mul_f32_e32 v24, v32, v24
	v_cvt_pk_bf16_f32 v24, v24, s0
	ds_write_b16 v23, v24 offset:1360
	v_lshlrev_b32_e32 v24, 16, v27
	v_mul_f32_e32 v24, v32, v24
	v_cvt_pk_bf16_f32 v24, v24, s0
	ds_write_b16 v23, v24 offset:1632
	v_and_b32_e32 v24, 0xffff0000, v27
	v_mul_f32_e32 v33, v32, v33
	v_mul_f32_e32 v24, v32, v24
	v_cvt_pk_bf16_f32 v33, v33, s0
	v_cvt_pk_bf16_f32 v24, v24, s0
	ds_write_b16 v23, v33
	ds_write_b16 v23, v24 offset:1904
	ds_write_b16 v23, v28 offset:34816
	ds_write_b16_d16_hi v23, v28 offset:35088
	ds_write_b16 v23, v29 offset:35360
	ds_write_b16_d16_hi v23, v29 offset:35632
	ds_write_b16 v23, v30 offset:35904
	ds_write_b16_d16_hi v23, v30 offset:36176
	ds_write_b16 v23, v31 offset:36448
	ds_write_b16_d16_hi v23, v31 offset:36720
	v_or_b32_e32 v23, 0x50, v10
	v_or_b32_e32 v24, v0, v23
	v_mad_u64_u32 v[24:25], s[8:9], v24, s14, v[2:3]
	v_mad_i32_i24 v25, v1, s14, v25
	v_lshl_add_u64 v[24:25], v[24:25], 0, v[160:161]
	v_lshl_add_u64 v[28:29], v[24:25], 0, v[4:5]
	global_load_dwordx4 v[24:27], v[28:29], off offset:1024
	s_nop 0
	global_load_dwordx4 v[28:31], v[28:29], off offset:2048
	v_bitop3_b32 v44, v9, s7, 15 bitop3:0x6c
	v_cvt_f32_ubyte0_e32 v44, v44
	v_mul_f32_e32 v44, v7, v44
	v_exp_f32_e32 v44, v44
	v_lshl_add_u32 v35, v35, 1, v8
	s_movk_i32 s7, 0x4f
	s_waitcnt vmcnt(6) lgkmcnt(0)
	v_lshlrev_b32_e32 v45, 16, v36
	v_and_b32_e32 v36, 0xffff0000, v36
	v_mul_f32_e32 v36, v44, v36
	v_cvt_pk_bf16_f32 v36, v36, s0
	ds_write_b16 v35, v36 offset:272
	v_lshlrev_b32_e32 v36, 16, v37
	v_mul_f32_e32 v36, v44, v36
	v_cvt_pk_bf16_f32 v36, v36, s0
	ds_write_b16 v35, v36 offset:544
	v_and_b32_e32 v36, 0xffff0000, v37
	v_mul_f32_e32 v36, v44, v36
	v_cvt_pk_bf16_f32 v36, v36, s0
	ds_write_b16 v35, v36 offset:816
	v_lshlrev_b32_e32 v36, 16, v38
	v_mul_f32_e32 v36, v44, v36
	v_cvt_pk_bf16_f32 v36, v36, s0
	ds_write_b16 v35, v36 offset:1088
	v_and_b32_e32 v36, 0xffff0000, v38
	v_mul_f32_e32 v36, v44, v36
	v_cvt_pk_bf16_f32 v36, v36, s0
	ds_write_b16 v35, v36 offset:1360
	v_lshlrev_b32_e32 v36, 16, v39
	v_mul_f32_e32 v36, v44, v36
	v_cvt_pk_bf16_f32 v36, v36, s0
	ds_write_b16 v35, v36 offset:1632
	v_and_b32_e32 v36, 0xffff0000, v39
	v_mul_f32_e32 v45, v44, v45
	v_mul_f32_e32 v36, v44, v36
	v_cvt_pk_bf16_f32 v45, v45, s0
	v_cvt_pk_bf16_f32 v36, v36, s0
	ds_write_b16 v35, v45
	ds_write_b16 v35, v36 offset:1904
	ds_write_b16 v35, v40 offset:34816
	ds_write_b16_d16_hi v35, v40 offset:35088
	ds_write_b16 v35, v41 offset:35360
	ds_write_b16_d16_hi v35, v41 offset:35632
	ds_write_b16 v35, v42 offset:35904
	ds_write_b16_d16_hi v35, v42 offset:36176
	ds_write_b16 v35, v43 offset:36448
	ds_write_b16_d16_hi v35, v43 offset:36720
	v_or_b32_e32 v35, 0x60, v10
	v_or_b32_e32 v36, v0, v35
	v_mad_u64_u32 v[36:37], s[8:9], v36, s14, v[2:3]
	v_mad_i32_i24 v37, v1, s14, v37
	v_lshl_add_u64 v[36:37], v[36:37], 0, v[160:161]
	v_lshl_add_u64 v[40:41], v[36:37], 0, v[4:5]
	global_load_dwordx4 v[36:39], v[40:41], off offset:1024
	s_nop 0
	global_load_dwordx4 v[40:43], v[40:41], off offset:2048
	v_bitop3_b32 v56, v9, s7, 15 bitop3:0x6c
	v_cvt_f32_ubyte0_e32 v56, v56
	v_mul_f32_e32 v56, v7, v56
	v_exp_f32_e32 v56, v56
	v_lshl_add_u32 v47, v47, 1, v8
	s_waitcnt vmcnt(6) lgkmcnt(0)
	v_lshlrev_b32_e32 v57, 16, v48
	v_and_b32_e32 v48, 0xffff0000, v48
	v_mul_f32_e32 v48, v56, v48
	v_cvt_pk_bf16_f32 v48, v48, s0
	ds_write_b16 v47, v48 offset:272
	v_lshlrev_b32_e32 v48, 16, v49
	v_mul_f32_e32 v48, v56, v48
	v_cvt_pk_bf16_f32 v48, v48, s0
	ds_write_b16 v47, v48 offset:544
	v_and_b32_e32 v48, 0xffff0000, v49
	v_mul_f32_e32 v48, v56, v48
	v_cvt_pk_bf16_f32 v48, v48, s0
	ds_write_b16 v47, v48 offset:816
	v_lshlrev_b32_e32 v48, 16, v50
	v_mul_f32_e32 v48, v56, v48
	v_cvt_pk_bf16_f32 v48, v48, s0
	ds_write_b16 v47, v48 offset:1088
	v_and_b32_e32 v48, 0xffff0000, v50
	v_mul_f32_e32 v48, v56, v48
	v_cvt_pk_bf16_f32 v48, v48, s0
	ds_write_b16 v47, v48 offset:1360
	v_lshlrev_b32_e32 v48, 16, v51
	v_mul_f32_e32 v48, v56, v48
	v_cvt_pk_bf16_f32 v48, v48, s0
	ds_write_b16 v47, v48 offset:1632
	v_and_b32_e32 v48, 0xffff0000, v51
	v_mul_f32_e32 v57, v56, v57
	v_mul_f32_e32 v48, v56, v48
	v_cvt_pk_bf16_f32 v57, v57, s0
	v_cvt_pk_bf16_f32 v48, v48, s0
	ds_write_b16 v47, v57
	ds_write_b16 v47, v48 offset:1904
	ds_write_b16 v47, v52 offset:34816
	ds_write_b16_d16_hi v47, v52 offset:35088
	ds_write_b16 v47, v53 offset:35360
	ds_write_b16_d16_hi v47, v53 offset:35632
	ds_write_b16 v47, v54 offset:35904
	ds_write_b16_d16_hi v47, v54 offset:36176
	ds_write_b16 v47, v55 offset:36448
	ds_write_b16_d16_hi v47, v55 offset:36720
	v_bitop3_b32 v20, v9, 63, 15 bitop3:0x6c
	v_cvt_f32_ubyte0_e32 v20, v20
	v_mul_f32_e32 v20, v7, v20
	v_exp_f32_e32 v20, v20
	v_lshl_add_u32 v11, v11, 1, v8
	s_waitcnt vmcnt(4) lgkmcnt(0)
; DI float bf2f(unsigned h) { return __uint_as_float(h << 16); }
; DI float ex2(float x) { return __builtin_amdgcn_exp2f(x); }
; DI void ret_u_item(const Params& p, int b, int n, int h, char* smem) {
;     ...
;   for (int i = 0; i < 8; ++i) {
;     const int c = tid + 256 * i, row = c >> 4, ch = c & 15;
;     const uint4 kv = *(const uint4*)(zr + (t0 + row) * LDZR + 512 + h * 128 + ch * 8);
;     const uint4 vv = *(const uint4*)(zr + (t0 + row) * LDZR + 1024 + h * 128 + ch * 8);
;     const float te = ex2((float)(127 - row) * lg);
;     char* kb = sKt + (ch * 8) * 272 + row * 2; char* vb = sVt + (ch * 8) * 272 + row * 2;
;     *(u16*)(kb + 0 * 272) = f2bf(bf2f(kv.x & 0xffffu) * te); *(u16*)(kb + 1 * 272) = f2bf(bf2f(kv.x >> 16) * te);
;     *(u16*)(kb + 2 * 272) = f2bf(bf2f(kv.y & 0xffffu) * te); *(u16*)(kb + 3 * 272) = f2bf(bf2f(kv.y >> 16) * te);
;     *(u16*)(kb + 4 * 272) = f2bf(bf2f(kv.z & 0xffffu) * te); *(u16*)(kb + 5 * 272) = f2bf(bf2f(kv.z >> 16) * te);
;     *(u16*)(kb + 6 * 272) = f2bf(bf2f(kv.w & 0xffffu) * te); *(u16*)(kb + 7 * 272) = f2bf(bf2f(kv.w >> 16) * te);
;     *(u16*)(vb + 0 * 272) = (u16)(vv.x & 0xffffu); *(u16*)(vb + 1 * 272) = (u16)(vv.x >> 16);
;     *(u16*)(vb + 2 * 272) = (u16)(vv.y & 0xffffu); *(u16*)(vb + 3 * 272) = (u16)(vv.y >> 16);
;     *(u16*)(vb + 4 * 272) = (u16)(vv.z & 0xffffu); *(u16*)(vb + 5 * 272) = (u16)(vv.z >> 16);
;     *(u16*)(vb + 6 * 272) = (u16)(vv.w & 0xffffu); *(u16*)(vb + 7 * 272) = (u16)(vv.w >> 16);
;   }
;   __syncthreads();
	v_lshlrev_b32_e32 v21, 16, v12
	v_and_b32_e32 v12, 0xffff0000, v12
	v_mul_f32_e32 v12, v20, v12
	v_cvt_pk_bf16_f32 v12, v12, s0
	ds_write_b16 v11, v12 offset:272
	v_lshlrev_b32_e32 v12, 16, v13
	v_mul_f32_e32 v12, v20, v12
	v_cvt_pk_bf16_f32 v12, v12, s0
	ds_write_b16 v11, v12 offset:544
	v_and_b32_e32 v12, 0xffff0000, v13
	v_mul_f32_e32 v12, v20, v12
	v_cvt_pk_bf16_f32 v12, v12, s0
	ds_write_b16 v11, v12 offset:816
	v_lshlrev_b32_e32 v12, 16, v14
	v_mul_f32_e32 v12, v20, v12
	v_cvt_pk_bf16_f32 v12, v12, s0
	ds_write_b16 v11, v12 offset:1088
	v_and_b32_e32 v12, 0xffff0000, v14
	v_mul_f32_e32 v12, v20, v12
	v_cvt_pk_bf16_f32 v12, v12, s0
	ds_write_b16 v11, v12 offset:1360
	v_lshlrev_b32_e32 v12, 16, v15
	v_mul_f32_e32 v12, v20, v12
	v_cvt_pk_bf16_f32 v12, v12, s0
	ds_write_b16 v11, v12 offset:1632
	v_and_b32_e32 v12, 0xffff0000, v15
	v_mul_f32_e32 v21, v20, v21
	v_mul_f32_e32 v12, v20, v12
	v_cvt_pk_bf16_f32 v21, v21, s0
	v_cvt_pk_bf16_f32 v12, v12, s0
	ds_write_b16 v11, v21
	ds_write_b16 v11, v12 offset:1904
	ds_write_b16 v11, v16 offset:34816
	ds_write_b16_d16_hi v11, v16 offset:35088
	ds_write_b16 v11, v17 offset:35360
	ds_write_b16_d16_hi v11, v17 offset:35632
	ds_write_b16 v11, v18 offset:35904
	ds_write_b16_d16_hi v11, v18 offset:36176
	ds_write_b16 v11, v19 offset:36448
	ds_write_b16_d16_hi v11, v19 offset:36720
	v_bitop3_b32 v32, v9, 47, 15 bitop3:0x6c
	v_cvt_f32_ubyte0_e32 v32, v32
	v_mul_f32_e32 v32, v7, v32
	v_exp_f32_e32 v32, v32
	v_lshl_add_u32 v23, v23, 1, v8
	s_waitcnt vmcnt(2) lgkmcnt(0)
	v_lshlrev_b32_e32 v33, 16, v24
	v_and_b32_e32 v24, 0xffff0000, v24
	v_mul_f32_e32 v24, v32, v24
	v_cvt_pk_bf16_f32 v24, v24, s0
	ds_write_b16 v23, v24 offset:272
	v_lshlrev_b32_e32 v24, 16, v25
	v_mul_f32_e32 v24, v32, v24
	v_cvt_pk_bf16_f32 v24, v24, s0
	ds_write_b16 v23, v24 offset:544
	v_and_b32_e32 v24, 0xffff0000, v25
	v_mul_f32_e32 v24, v32, v24
	v_cvt_pk_bf16_f32 v24, v24, s0
	ds_write_b16 v23, v24 offset:816
	v_lshlrev_b32_e32 v24, 16, v26
	v_mul_f32_e32 v24, v32, v24
	v_cvt_pk_bf16_f32 v24, v24, s0
	ds_write_b16 v23, v24 offset:1088
	v_and_b32_e32 v24, 0xffff0000, v26
	v_mul_f32_e32 v24, v32, v24
	v_cvt_pk_bf16_f32 v24, v24, s0
	ds_write_b16 v23, v24 offset:1360
	v_lshlrev_b32_e32 v24, 16, v27
	v_mul_f32_e32 v24, v32, v24
	v_cvt_pk_bf16_f32 v24, v24, s0
	ds_write_b16 v23, v24 offset:1632
	v_and_b32_e32 v24, 0xffff0000, v27
	v_mul_f32_e32 v33, v32, v33
	v_mul_f32_e32 v24, v32, v24
	v_cvt_pk_bf16_f32 v33, v33, s0
	v_cvt_pk_bf16_f32 v24, v24, s0
	ds_write_b16 v23, v33
	ds_write_b16 v23, v24 offset:1904
	ds_write_b16 v23, v28 offset:34816
	ds_write_b16_d16_hi v23, v28 offset:35088
	ds_write_b16 v23, v29 offset:35360
	ds_write_b16_d16_hi v23, v29 offset:35632
	ds_write_b16 v23, v30 offset:35904
	ds_write_b16_d16_hi v23, v30 offset:36176
	ds_write_b16 v23, v31 offset:36448
	ds_write_b16_d16_hi v23, v31 offset:36720
	v_bitop3_b32 v44, v9, 31, 15 bitop3:0x6c
	v_cvt_f32_ubyte0_e32 v44, v44
	v_mul_f32_e32 v44, v7, v44
	v_exp_f32_e32 v44, v44
	v_lshl_add_u32 v35, v35, 1, v8
	s_waitcnt vmcnt(0) lgkmcnt(0)
	v_lshlrev_b32_e32 v45, 16, v36
	v_and_b32_e32 v36, 0xffff0000, v36
	v_mul_f32_e32 v36, v44, v36
	v_cvt_pk_bf16_f32 v36, v36, s0
	ds_write_b16 v35, v36 offset:272
	v_lshlrev_b32_e32 v36, 16, v37
	v_mul_f32_e32 v36, v44, v36
	v_cvt_pk_bf16_f32 v36, v36, s0
	ds_write_b16 v35, v36 offset:544
	v_and_b32_e32 v36, 0xffff0000, v37
	v_mul_f32_e32 v36, v44, v36
	v_cvt_pk_bf16_f32 v36, v36, s0
	ds_write_b16 v35, v36 offset:816
	v_lshlrev_b32_e32 v36, 16, v38
	v_mul_f32_e32 v36, v44, v36
	v_cvt_pk_bf16_f32 v36, v36, s0
	ds_write_b16 v35, v36 offset:1088
	v_and_b32_e32 v36, 0xffff0000, v38
	v_mul_f32_e32 v36, v44, v36
	v_cvt_pk_bf16_f32 v36, v36, s0
	ds_write_b16 v35, v36 offset:1360
	v_lshlrev_b32_e32 v36, 16, v39
	v_mul_f32_e32 v36, v44, v36
	v_or_b32_e32 v14, 0x70, v10
	v_cvt_pk_bf16_f32 v36, v36, s0
	v_or_b32_e32 v0, v0, v14
	ds_write_b16 v35, v36 offset:1632
	v_and_b32_e32 v36, 0xffff0000, v39
	v_mad_u64_u32 v[2:3], s[8:9], v0, s14, v[2:3]
	v_mul_f32_e32 v45, v44, v45
	v_mul_f32_e32 v36, v44, v36
	v_mad_i32_i24 v3, v1, s14, v3
	v_cvt_pk_bf16_f32 v45, v45, s0
	v_cvt_pk_bf16_f32 v36, v36, s0
	v_lshl_add_u64 v[0:1], v[2:3], 0, v[160:161]
	ds_write_b16 v35, v45
	ds_write_b16 v35, v36 offset:1904
	ds_write_b16 v35, v40 offset:34816
	ds_write_b16_d16_hi v35, v40 offset:35088
	ds_write_b16 v35, v41 offset:35360
	ds_write_b16_d16_hi v35, v41 offset:35632
	ds_write_b16 v35, v42 offset:35904
	ds_write_b16_d16_hi v35, v42 offset:36176
	ds_write_b16 v35, v43 offset:36448
	ds_write_b16_d16_hi v35, v43 offset:36720
	v_lshl_add_u64 v[4:5], v[0:1], 0, v[4:5]
	flat_load_dwordx4 v[0:3], v[4:5] offset:1024
	flat_load_dwordx4 v[10:13], v[4:5] offset:2048
	v_bitop3_b32 v4, v9, 15, v9 bitop3:0xc
	v_cvt_f32_ubyte0_e32 v4, v4
	v_mul_f32_e32 v4, v7, v4
	v_exp_f32_e32 v4, v4
	v_lshl_add_u32 v5, v14, 1, v8
	s_waitcnt vmcnt(0) lgkmcnt(0)
	v_lshlrev_b32_e32 v7, 16, v0
	v_and_b32_e32 v0, 0xffff0000, v0
	v_mul_f32_e32 v0, v4, v0
	v_cvt_pk_bf16_f32 v0, v0, s0
	ds_write_b16 v5, v0 offset:272
	v_lshlrev_b32_e32 v0, 16, v1
	v_mul_f32_e32 v0, v4, v0
	v_cvt_pk_bf16_f32 v0, v0, s0
	ds_write_b16 v5, v0 offset:544
	v_and_b32_e32 v0, 0xffff0000, v1
	v_mul_f32_e32 v0, v4, v0
	v_cvt_pk_bf16_f32 v0, v0, s0
	ds_write_b16 v5, v0 offset:816
	v_lshlrev_b32_e32 v0, 16, v2
	v_mul_f32_e32 v0, v4, v0
	v_cvt_pk_bf16_f32 v0, v0, s0
	ds_write_b16 v5, v0 offset:1088
	v_and_b32_e32 v0, 0xffff0000, v2
	v_mul_f32_e32 v0, v4, v0
	v_cvt_pk_bf16_f32 v0, v0, s0
	ds_write_b16 v5, v0 offset:1360
	v_lshlrev_b32_e32 v0, 16, v3
	v_mul_f32_e32 v0, v4, v0
	v_cvt_pk_bf16_f32 v0, v0, s0
	ds_write_b16 v5, v0 offset:1632
	v_and_b32_e32 v0, 0xffff0000, v3
	v_mul_f32_e32 v7, v4, v7
	v_mul_f32_e32 v0, v4, v0
	v_cvt_pk_bf16_f32 v7, v7, s0
	v_cvt_pk_bf16_f32 v0, v0, s0
	ds_write_b16 v5, v7
	ds_write_b16 v5, v0 offset:1904
	ds_write_b16 v5, v10 offset:34816
	ds_write_b16_d16_hi v5, v10 offset:35088
	ds_write_b16 v5, v11 offset:35360
	ds_write_b16_d16_hi v5, v11 offset:35632
	ds_write_b16 v5, v12 offset:35904
	ds_write_b16_d16_hi v5, v12 offset:36176
	ds_write_b16 v5, v13 offset:36448
	ds_write_b16_d16_hi v5, v13 offset:36720
	v_lshrrev_b32_e32 v0, 1, v6
	v_and_b32_e32 v72, 64, v0
	v_and_or_b32 v0, v6, 31, v72
	v_lshl_add_u32 v4, v71, 4, v67
	v_mad_u32_u24 v73, v0, s20, v4
	s_waitcnt lgkmcnt(0)
	s_barrier
; #define MFMA(a, b, c) __builtin_amdgcn_mfma_f32_32x32x16_bf16((a), (b), (c), 0, 0, 0)
; DI int crow(int r, int hf) { return (r & 3) + 8 * (r >> 2) + 4 * hf; }
; DI f32x16 zero16() { f32x16 z; for (int i = 0; i < 16; ++i) z[i] = 0.f; return z; }
; DI void ret_u_item(const Params& p, int b, int n, int h, char* smem) {
;     ...
;   f32x16 acc[2][2];
; #pragma unroll
;   for (int i = 0; i < 2; ++i)
; #pragma unroll
;     for (int jn = 0; jn < 2; ++jn) acc[i][jn] = zero16();
; #pragma unroll
;   for (int s = 0; s < 8; ++s) {
;     bf16x8 af[2], bfr[2];
; #pragma unroll
;     for (int i = 0; i < 2; ++i) af[i] = *(const bf16x8*)(sVt + (wm * 64 + i * 32 + l32) * 272 + (s * 16 + hf * 8) * 2);
; #pragma unroll
;     for (int jn = 0; jn < 2; ++jn) bfr[jn] = *(const bf16x8*)(sKt + (wn * 64 + jn * 32 + l32) * 272 + (s * 16 + hf * 8) * 2);
; #pragma unroll
;     for (int i = 0; i < 2; ++i)
; #pragma unroll
;       for (int jn = 0; jn < 2; ++jn) acc[i][jn] = MFMA(af[i], bfr[jn], acc[i][jn]);
;   }
;   float* Ub = U + ((size_t)((b * 4 + h) * 128 + n)) * 16384;
; #pragma unroll
;   for (int i = 0; i < 2; ++i)
; #pragma unroll
;     for (int jn = 0; jn < 2; ++jn)
; #pragma unroll
;       for (int r = 0; r < 16; ++r) Ub[(wm * 64 + i * 32 + crow(r, hf)) * 128 + wn * 64 + jn * 32 + l32] = acc[i][jn][r];
	ds_read_b128 v[0:3], v73 offset:43520
	v_mad_u32_u24 v90, v70, s20, v4
	ds_read_b128 v[4:7], v90 offset:8704
	ds_read_b128 v[8:11], v73 offset:34816
	ds_read_b128 v[74:77], v73 offset:34848
	ds_read_b128 v[12:15], v90
	ds_read_b128 v[78:81], v90 offset:32
	s_waitcnt lgkmcnt(1)
	v_mfma_f32_32x32x16_bf16 v[48:63], v[8:11], v[12:15], 0
	ds_read_b128 v[82:85], v73 offset:43552
	ds_read_b128 v[86:89], v90 offset:8736
	v_lshlrev_b32_e32 v72, 7, v72
	v_lshl_or_b32 v71, v71, 9, v72
	v_or_b32_e32 v72, v71, v70
	v_lshlrev_b32_e32 v160, 2, v72
	v_mfma_f32_32x32x16_bf16 v[32:47], v[8:11], v[4:7], 0
	v_mfma_f32_32x32x16_bf16 v[16:31], v[0:3], v[12:15], 0
	v_mfma_f32_32x32x16_bf16 v[0:15], v[0:3], v[4:7], 0
	s_waitcnt lgkmcnt(2)
	v_mfma_f32_32x32x16_bf16 v[48:63], v[74:77], v[78:81], v[48:63]
	s_waitcnt lgkmcnt(0)
	v_mfma_f32_32x32x16_bf16 v[32:47], v[74:77], v[86:89], v[32:47]
	v_mfma_f32_32x32x16_bf16 v[16:31], v[82:85], v[78:81], v[16:31]
	v_mfma_f32_32x32x16_bf16 v[0:15], v[82:85], v[86:89], v[0:15]
	ds_read_b128 v[74:77], v73 offset:34880
	ds_read_b128 v[78:81], v73 offset:43584
	ds_read_b128 v[82:85], v90 offset:64
	ds_read_b128 v[86:89], v90 offset:8768
	s_waitcnt lgkmcnt(1)
	v_mfma_f32_32x32x16_bf16 v[48:63], v[74:77], v[82:85], v[48:63]
	s_waitcnt lgkmcnt(0)
	v_mfma_f32_32x32x16_bf16 v[32:47], v[74:77], v[86:89], v[32:47]
	v_mfma_f32_32x32x16_bf16 v[16:31], v[78:81], v[82:85], v[16:31]
	v_mfma_f32_32x32x16_bf16 v[0:15], v[78:81], v[86:89], v[0:15]
	ds_read_b128 v[74:77], v73 offset:34912
	ds_read_b128 v[78:81], v73 offset:43616
	ds_read_b128 v[82:85], v90 offset:96
	ds_read_b128 v[86:89], v90 offset:8800
	s_waitcnt lgkmcnt(1)
	v_mfma_f32_32x32x16_bf16 v[48:63], v[74:77], v[82:85], v[48:63]
	s_waitcnt lgkmcnt(0)
	v_mfma_f32_32x32x16_bf16 v[32:47], v[74:77], v[86:89], v[32:47]
	v_mfma_f32_32x32x16_bf16 v[16:31], v[78:81], v[82:85], v[16:31]
	v_mfma_f32_32x32x16_bf16 v[0:15], v[78:81], v[86:89], v[0:15]
	ds_read_b128 v[74:77], v73 offset:34944
	ds_read_b128 v[78:81], v73 offset:43648
	ds_read_b128 v[82:85], v90 offset:128
	ds_read_b128 v[86:89], v90 offset:8832
	s_waitcnt lgkmcnt(1)
	v_mfma_f32_32x32x16_bf16 v[48:63], v[74:77], v[82:85], v[48:63]
	s_waitcnt lgkmcnt(0)
	v_mfma_f32_32x32x16_bf16 v[32:47], v[74:77], v[86:89], v[32:47]
	v_mfma_f32_32x32x16_bf16 v[16:31], v[78:81], v[82:85], v[16:31]
	v_mfma_f32_32x32x16_bf16 v[0:15], v[78:81], v[86:89], v[0:15]
	ds_read_b128 v[74:77], v73 offset:34976
	ds_read_b128 v[78:81], v73 offset:43680
	ds_read_b128 v[82:85], v90 offset:160
	ds_read_b128 v[86:89], v90 offset:8864
	s_waitcnt lgkmcnt(1)
	v_mfma_f32_32x32x16_bf16 v[48:63], v[74:77], v[82:85], v[48:63]
	s_waitcnt lgkmcnt(0)
	v_mfma_f32_32x32x16_bf16 v[32:47], v[74:77], v[86:89], v[32:47]
	v_mfma_f32_32x32x16_bf16 v[16:31], v[78:81], v[82:85], v[16:31]
	v_mfma_f32_32x32x16_bf16 v[0:15], v[78:81], v[86:89], v[0:15]
	ds_read_b128 v[74:77], v73 offset:35008
	ds_read_b128 v[78:81], v73 offset:43712
	ds_read_b128 v[82:85], v90 offset:192
	ds_read_b128 v[86:89], v90 offset:8896
	s_waitcnt lgkmcnt(1)
	v_mfma_f32_32x32x16_bf16 v[48:63], v[74:77], v[82:85], v[48:63]
	s_waitcnt lgkmcnt(0)
	v_mfma_f32_32x32x16_bf16 v[32:47], v[74:77], v[86:89], v[32:47]
	v_mfma_f32_32x32x16_bf16 v[16:31], v[78:81], v[82:85], v[16:31]
	v_mfma_f32_32x32x16_bf16 v[0:15], v[78:81], v[86:89], v[0:15]
	ds_read_b128 v[74:77], v73 offset:35040
	ds_read_b128 v[78:81], v73 offset:43744
	ds_read_b128 v[82:85], v90 offset:224
	ds_read_b128 v[86:89], v90 offset:8928
	v_and_b32_e32 v73, 0xfffffe00, v68
	v_or3_b32 v64, v65, v73, v64
	v_ashrrev_i32_e32 v65, 31, v64
	v_lshlrev_b64 v[64:65], 16, v[64:65]
	v_lshl_add_u64 v[64:65], s[0:1], 0, v[64:65]
	v_lshl_add_u64 v[64:65], v[64:65], 0, s[22:23]
	s_waitcnt lgkmcnt(1)
	v_mfma_f32_32x32x16_bf16 v[48:63], v[74:77], v[82:85], v[48:63]
	v_lshl_add_u64 v[72:73], v[64:65], 0, v[160:161]
	s_nop 10
	flat_store_dword v[72:73], v48
	flat_store_dword v[72:73], v49 offset:512
	flat_store_dword v[72:73], v50 offset:1024
	flat_store_dword v[72:73], v51 offset:1536
	v_or_b32_e32 v50, 0x400, v71
	v_or_b32_e32 v48, v50, v70
	v_lshlrev_b32_e32 v160, 2, v48
	v_lshl_add_u64 v[48:49], v[64:65], 0, v[160:161]
	v_or_b32_e32 v51, 0x480, v71
	flat_store_dword v[48:49], v52
	v_or_b32_e32 v48, v51, v70
	v_lshlrev_b32_e32 v160, 2, v48
	v_lshl_add_u64 v[48:49], v[64:65], 0, v[160:161]
	v_or_b32_e32 v52, 0x500, v71
	flat_store_dword v[48:49], v53
	v_or_b32_e32 v48, v52, v70
	v_lshlrev_b32_e32 v160, 2, v48
	v_lshl_add_u64 v[48:49], v[64:65], 0, v[160:161]
	v_or_b32_e32 v53, 0x580, v71
	flat_store_dword v[48:49], v54
	v_or_b32_e32 v48, v53, v70
	v_lshlrev_b32_e32 v160, 2, v48
	v_lshl_add_u64 v[48:49], v[64:65], 0, v[160:161]
	v_or_b32_e32 v54, 0x800, v71
	flat_store_dword v[48:49], v55
	v_or_b32_e32 v48, v54, v70
	v_lshlrev_b32_e32 v160, 2, v48
	v_lshl_add_u64 v[48:49], v[64:65], 0, v[160:161]
	v_or_b32_e32 v55, 0x880, v71
	flat_store_dword v[48:49], v56
	v_or_b32_e32 v48, v55, v70
	v_lshlrev_b32_e32 v160, 2, v48
	v_lshl_add_u64 v[48:49], v[64:65], 0, v[160:161]
	v_or_b32_e32 v56, 0x900, v71
	flat_store_dword v[48:49], v57
	v_or_b32_e32 v48, v56, v70
	v_lshlrev_b32_e32 v160, 2, v48
	v_lshl_add_u64 v[48:49], v[64:65], 0, v[160:161]
	v_or_b32_e32 v57, 0x980, v71
	flat_store_dword v[48:49], v58
	v_or_b32_e32 v48, v57, v70
	v_lshlrev_b32_e32 v160, 2, v48
	v_lshl_add_u64 v[48:49], v[64:65], 0, v[160:161]
	v_or_b32_e32 v58, 0xc00, v71
	flat_store_dword v[48:49], v59
	v_or_b32_e32 v48, v58, v70
	v_lshlrev_b32_e32 v160, 2, v48
	v_lshl_add_u64 v[48:49], v[64:65], 0, v[160:161]
	v_or_b32_e32 v59, 0xc80, v71
	flat_store_dword v[48:49], v60
	v_or_b32_e32 v48, v59, v70
	v_lshlrev_b32_e32 v160, 2, v48
	s_waitcnt lgkmcnt(0)
; DI int crow(int r, int hf) { return (r & 3) + 8 * (r >> 2) + 4 * hf; }
; DI void ret_u_item(const Params& p, int b, int n, int h, char* smem) {
;     ...
;   float* Ub = U + ((size_t)((b * 4 + h) * 128 + n)) * 16384;
; #pragma unroll
;   for (int i = 0; i < 2; ++i)
; #pragma unroll
;     for (int jn = 0; jn < 2; ++jn)
; #pragma unroll
;       for (int r = 0; r < 16; ++r) Ub[(wm * 64 + i * 32 + crow(r, hf)) * 128 + wn * 64 + jn * 32 + l32] = acc[i][jn][r];
	v_mfma_f32_32x32x16_bf16 v[32:47], v[74:77], v[86:89], v[32:47]
	v_lshl_add_u64 v[48:49], v[64:65], 0, v[160:161]
	v_or_b32_e32 v60, 0xd00, v71
	flat_store_dword v[48:49], v61
	v_or_b32_e32 v48, v60, v70
	v_lshlrev_b32_e32 v160, 2, v48
	v_lshl_add_u64 v[48:49], v[64:65], 0, v[160:161]
	v_or_b32_e32 v61, 0xd80, v71
	flat_store_dword v[48:49], v62
	v_or_b32_e32 v48, v61, v70
	v_lshlrev_b32_e32 v160, 2, v48
	v_lshl_add_u64 v[48:49], v[64:65], 0, v[160:161]
	flat_store_dword v[48:49], v63
	flat_store_dword v[72:73], v32 offset:128
	v_or_b32_e32 v32, v71, v69
	v_lshlrev_b32_e32 v160, 2, v32
	v_or_b32_e32 v32, v50, v69
	v_lshl_add_u64 v[48:49], v[64:65], 0, v[160:161]
	v_lshlrev_b32_e32 v160, 2, v32
	flat_store_dword v[48:49], v33 offset:512
	flat_store_dword v[48:49], v34 offset:1024
	flat_store_dword v[48:49], v35 offset:1536
	v_lshl_add_u64 v[32:33], v[64:65], 0, v[160:161]
	flat_store_dword v[32:33], v36
	v_or_b32_e32 v32, v51, v69
	v_lshlrev_b32_e32 v160, 2, v32
	v_lshl_add_u64 v[32:33], v[64:65], 0, v[160:161]
	flat_store_dword v[32:33], v37
	v_or_b32_e32 v32, v52, v69
	v_lshlrev_b32_e32 v160, 2, v32
	v_lshl_add_u64 v[32:33], v[64:65], 0, v[160:161]
	flat_store_dword v[32:33], v38
	v_or_b32_e32 v32, v53, v69
	v_lshlrev_b32_e32 v160, 2, v32
	v_lshl_add_u64 v[32:33], v[64:65], 0, v[160:161]
	flat_store_dword v[32:33], v39
	v_or_b32_e32 v32, v54, v69
	v_lshlrev_b32_e32 v160, 2, v32
	v_lshl_add_u64 v[32:33], v[64:65], 0, v[160:161]
	flat_store_dword v[32:33], v40
	v_or_b32_e32 v32, v55, v69
	v_lshlrev_b32_e32 v160, 2, v32
	v_lshl_add_u64 v[32:33], v[64:65], 0, v[160:161]
	flat_store_dword v[32:33], v41
	v_or_b32_e32 v32, v56, v69
	v_lshlrev_b32_e32 v160, 2, v32
	v_lshl_add_u64 v[32:33], v[64:65], 0, v[160:161]
	flat_store_dword v[32:33], v42
	v_or_b32_e32 v32, v57, v69
	v_lshlrev_b32_e32 v160, 2, v32
	v_lshl_add_u64 v[32:33], v[64:65], 0, v[160:161]
	flat_store_dword v[32:33], v43
	v_or_b32_e32 v32, v58, v69
	v_lshlrev_b32_e32 v160, 2, v32
	v_lshl_add_u64 v[32:33], v[64:65], 0, v[160:161]
	flat_store_dword v[32:33], v44
	v_or_b32_e32 v32, v59, v69
	v_lshlrev_b32_e32 v160, 2, v32
	v_lshl_add_u64 v[32:33], v[64:65], 0, v[160:161]
	flat_store_dword v[32:33], v45
	v_or_b32_e32 v32, v60, v69
	v_mfma_f32_32x32x16_bf16 v[16:31], v[78:81], v[82:85], v[16:31]
	v_lshlrev_b32_e32 v160, 2, v32
	v_lshl_add_u64 v[32:33], v[64:65], 0, v[160:161]
	flat_store_dword v[32:33], v46
	v_or_b32_e32 v32, v61, v69
	v_lshlrev_b32_e32 v160, 2, v32
	v_lshl_add_u64 v[32:33], v[64:65], 0, v[160:161]
	v_or_b32_e32 v34, 0x1000, v71
	flat_store_dword v[32:33], v47
	v_or_b32_e32 v32, v34, v70
	v_lshlrev_b32_e32 v160, 2, v32
	v_lshl_add_u64 v[32:33], v[64:65], 0, v[160:161]
	v_or_b32_e32 v35, 0x1080, v71
	flat_store_dword v[32:33], v16
	v_or_b32_e32 v16, v35, v70
	v_lshlrev_b32_e32 v160, 2, v16
	v_lshl_add_u64 v[32:33], v[64:65], 0, v[160:161]
	flat_store_dword v[32:33], v17
	v_or_b32_e32 v32, 0x1100, v71
	v_or_b32_e32 v16, v32, v70
	v_lshlrev_b32_e32 v160, 2, v16
	v_lshl_add_u64 v[16:17], v[64:65], 0, v[160:161]
	flat_store_dword v[16:17], v18
	v_or_b32_e32 v18, 0x1180, v71
	v_or_b32_e32 v16, v18, v70
	v_lshlrev_b32_e32 v160, 2, v16
	v_lshl_add_u64 v[16:17], v[64:65], 0, v[160:161]
	flat_store_dword v[16:17], v19
	v_or_b32_e32 v19, 0x1400, v71
	v_or_b32_e32 v16, v19, v70
	v_lshlrev_b32_e32 v160, 2, v16
	v_lshl_add_u64 v[16:17], v[64:65], 0, v[160:161]
	flat_store_dword v[16:17], v20
	v_or_b32_e32 v20, 0x1480, v71
	v_or_b32_e32 v16, v20, v70
	v_lshlrev_b32_e32 v160, 2, v16
	v_lshl_add_u64 v[16:17], v[64:65], 0, v[160:161]
	flat_store_dword v[16:17], v21
	v_or_b32_e32 v21, 0x1500, v71
	v_or_b32_e32 v16, v21, v70
	v_lshlrev_b32_e32 v160, 2, v16
	v_lshl_add_u64 v[16:17], v[64:65], 0, v[160:161]
	flat_store_dword v[16:17], v22
	v_or_b32_e32 v22, 0x1580, v71
	v_or_b32_e32 v16, v22, v70
; DI int crow(int r, int hf) { return (r & 3) + 8 * (r >> 2) + 4 * hf; }
; DI int opqv(int x) { asm volatile("" : "+v"(x)); return x; }
; DI char* opq(char* p) { asm volatile("" : "+s"(p)); return p; }
; DI void ret_u_item(const Params& p, int b, int n, int h, char* smem) {
;     ...
;   float* Ub = U + ((size_t)((b * 4 + h) * 128 + n)) * 16384;
; #pragma unroll
;   for (int i = 0; i < 2; ++i)
; #pragma unroll
;     for (int jn = 0; jn < 2; ++jn)
; #pragma unroll
;       for (int r = 0; r < 16; ++r) Ub[(wm * 64 + i * 32 + crow(r, hf)) * 128 + wn * 64 + jn * 32 + l32] = acc[i][jn][r];
;   __syncthreads();
; }
; DI void rec_state_phase(const Params& p, int j, char* smem) {
;   const int tid = opqv(threadIdx.x), lane = tid & 63, w = tid >> 6, wm = w >> 2, wn = w & 3, l32 = lane & 31, hf = lane >> 5;
;   char* ws = opq(p.ws);
;   {
;     const int half = opqv(threadIdx.x) >> 8;
;     char* sm = smem + half * HALF_SMEM;
;     for (int it = blockIdx.x; it < 512; it += gridDim.x) { const int item = it * 2 + half; ret_u_item(p, item >> 9, (item >> 2) & 127, item & 3, sm); }
	v_lshlrev_b32_e32 v160, 2, v16
	v_lshl_add_u64 v[16:17], v[64:65], 0, v[160:161]
	flat_store_dword v[16:17], v23
	v_or_b32_e32 v23, 0x1800, v71
	v_or_b32_e32 v16, v23, v70
	v_lshlrev_b32_e32 v160, 2, v16
	v_lshl_add_u64 v[16:17], v[64:65], 0, v[160:161]
	flat_store_dword v[16:17], v24
	v_or_b32_e32 v24, 0x1880, v71
	v_or_b32_e32 v16, v24, v70
	v_lshlrev_b32_e32 v160, 2, v16
	v_lshl_add_u64 v[16:17], v[64:65], 0, v[160:161]
	flat_store_dword v[16:17], v25
	v_or_b32_e32 v25, 0x1900, v71
	v_or_b32_e32 v16, v25, v70
	v_lshlrev_b32_e32 v160, 2, v16
	v_lshl_add_u64 v[16:17], v[64:65], 0, v[160:161]
	flat_store_dword v[16:17], v26
	v_or_b32_e32 v26, 0x1980, v71
	v_or_b32_e32 v16, v26, v70
	v_lshlrev_b32_e32 v160, 2, v16
	v_lshl_add_u64 v[16:17], v[64:65], 0, v[160:161]
	flat_store_dword v[16:17], v27
	v_or_b32_e32 v27, 0x1c00, v71
	v_or_b32_e32 v16, v27, v70
	v_lshlrev_b32_e32 v160, 2, v16
	v_lshl_add_u64 v[16:17], v[64:65], 0, v[160:161]
	flat_store_dword v[16:17], v28
	v_or_b32_e32 v28, 0x1c80, v71
	v_or_b32_e32 v16, v28, v70
	v_lshlrev_b32_e32 v160, 2, v16
	v_lshl_add_u64 v[16:17], v[64:65], 0, v[160:161]
	flat_store_dword v[16:17], v29
	v_or_b32_e32 v29, 0x1d00, v71
	v_or_b32_e32 v16, v29, v70
	v_lshlrev_b32_e32 v160, 2, v16
	v_mfma_f32_32x32x16_bf16 v[0:15], v[78:81], v[86:89], v[0:15]
	v_lshl_add_u64 v[16:17], v[64:65], 0, v[160:161]
	flat_store_dword v[16:17], v30
	v_or_b32_e32 v30, 0x1d80, v71
	v_or_b32_e32 v16, v30, v70
	v_lshlrev_b32_e32 v160, 2, v16
	v_lshl_add_u64 v[16:17], v[64:65], 0, v[160:161]
	flat_store_dword v[16:17], v31
	v_or_b32_e32 v16, v34, v69
	v_lshlrev_b32_e32 v160, 2, v16
	v_lshl_add_u64 v[16:17], v[64:65], 0, v[160:161]
	s_nop 1
	flat_store_dword v[16:17], v0
	v_or_b32_e32 v0, v35, v69
	v_lshlrev_b32_e32 v160, 2, v0
	v_or_b32_e32 v0, v32, v69
	v_lshl_add_u64 v[16:17], v[64:65], 0, v[160:161]
	v_lshlrev_b32_e32 v160, 2, v0
	flat_store_dword v[16:17], v1
	v_lshl_add_u64 v[0:1], v[64:65], 0, v[160:161]
	flat_store_dword v[0:1], v2
	v_or_b32_e32 v0, v18, v69
	v_lshlrev_b32_e32 v160, 2, v0
	v_lshl_add_u64 v[0:1], v[64:65], 0, v[160:161]
	flat_store_dword v[0:1], v3
	v_or_b32_e32 v0, v19, v69
	v_lshlrev_b32_e32 v160, 2, v0
	v_lshl_add_u64 v[0:1], v[64:65], 0, v[160:161]
	flat_store_dword v[0:1], v4
	v_or_b32_e32 v0, v20, v69
	v_lshlrev_b32_e32 v160, 2, v0
	v_lshl_add_u64 v[0:1], v[64:65], 0, v[160:161]
	flat_store_dword v[0:1], v5
	v_or_b32_e32 v0, v21, v69
	v_lshlrev_b32_e32 v160, 2, v0
	v_lshl_add_u64 v[0:1], v[64:65], 0, v[160:161]
	flat_store_dword v[0:1], v6
	v_or_b32_e32 v0, v22, v69
	v_lshlrev_b32_e32 v160, 2, v0
	v_lshl_add_u64 v[0:1], v[64:65], 0, v[160:161]
	flat_store_dword v[0:1], v7
	v_or_b32_e32 v0, v23, v69
	v_lshlrev_b32_e32 v160, 2, v0
	v_lshl_add_u64 v[0:1], v[64:65], 0, v[160:161]
	flat_store_dword v[0:1], v8
	v_or_b32_e32 v0, v24, v69
	v_lshlrev_b32_e32 v160, 2, v0
	v_lshl_add_u64 v[0:1], v[64:65], 0, v[160:161]
	flat_store_dword v[0:1], v9
	v_or_b32_e32 v0, v25, v69
	v_lshlrev_b32_e32 v160, 2, v0
	v_lshl_add_u64 v[0:1], v[64:65], 0, v[160:161]
	flat_store_dword v[0:1], v10
	v_or_b32_e32 v0, v26, v69
	v_lshlrev_b32_e32 v160, 2, v0
	v_lshl_add_u64 v[0:1], v[64:65], 0, v[160:161]
	flat_store_dword v[0:1], v11
	v_or_b32_e32 v0, v27, v69
	v_lshlrev_b32_e32 v160, 2, v0
	v_lshl_add_u64 v[0:1], v[64:65], 0, v[160:161]
	flat_store_dword v[0:1], v12
	v_or_b32_e32 v0, v28, v69
	v_lshlrev_b32_e32 v160, 2, v0
	v_lshl_add_u64 v[0:1], v[64:65], 0, v[160:161]
	flat_store_dword v[0:1], v13
	v_or_b32_e32 v0, v29, v69
	v_lshlrev_b32_e32 v160, 2, v0
	v_lshl_add_u64 v[0:1], v[64:65], 0, v[160:161]
	flat_store_dword v[0:1], v14
	v_or_b32_e32 v0, v30, v69
	v_lshlrev_b32_e32 v160, 2, v0
	v_lshl_add_u64 v[0:1], v[64:65], 0, v[160:161]
	v_add_u32_e32 v68, s12, v68
	flat_store_dword v[0:1], v15
	s_waitcnt lgkmcnt(0)
	s_barrier
	s_cbranch_scc0 .LBB0_766
